# chain: each wave's 4 wave-private VT LDS-DMA pieces for step n+1 issued right after its VT reads of step n-1 (a full step earlier); step top issues only the 5 PD pieces + decay; top wait vmcnt(20)
# speedup vs baseline: 1.0226x; 1.0070x over previous
; #define LAS __attribute__((address_space(3)))
; #define RD_QD(dst, s0) _Pragma("unroll") for (int s_ = 0; s_ < 4; ++s_) { dst[s_] = *(const LAS bf16x8*)(B + CH_QD + i0 * 256 + (((2 * ((s0) + s_) + hi) ^ (i0 & 15)) << 4)); \
;                 dst[4 + s_] = *(const LAS bf16x8*)(B + CH_QD + i1 * 256 + (((2 * ((s0) + s_) + hi) ^ (i1 & 15)) << 4)); }
; #define DECAY(db_) do { f32x4 dc_[4]; _Pragma("unroll") for (int a4_ = 0; a4_ < 4; ++a4_) dc_[a4_] = *(const LAS f32x4*)(B + CH_DEC + ((db_) * 32 + 8 * a4_ + 4 * hi) * 4); \
;                 _Pragma("unroll") for (int a4_ = 0; a4_ < 4; ++a4_) _Pragma("unroll") for (int b4_ = 0; b4_ < 4; ++b4_) T[db_][a4_ * 4 + b4_] *= dc_[a4_][b4_]; } while (0)
; DI void phase_gla_chain(const Params& P, int l, int task0, int ntask_stride, LAS unsigned char* lds) {
;     ...
;             const int i0 = r32, i1 = 32 + r32; const int vv = wid * 32 + r32;
;             bf16x8 fa[8], fb[8], vf[4];
;             f32x16 o[2]; for (int x = 0; x < 16; ++x) { o[0][x] = 0.f; o[1][x] = 0.f; }
;     ...
;             RD_QD(fa, 0);
; #pragma unroll
;             for (int ks = 0; ks < 4; ++ks) vf[ks] = *(const LAS bf16x8*)(B + CH_VT + vv * 128 + (((2 * ks + hi) ^ ((vv >> 1) & 7)) << 4));
;             __builtin_amdgcn_sched_barrier(0);
;             RD_QD(fb, 4);
;             __builtin_amdgcn_sched_barrier(0);
;             MM_QD(fa, 0);
;             DECAY(0); DECAY(1);
;             __builtin_amdgcn_sched_barrier(0);
; #pragma unroll
;             for (int ks = 0; ks < 4; ++ks) { fa[ks] = *(const LAS bf16x8*)(B + CH_AM + i0 * 128 + (((2 * ks + hi) ^ ((i0 >> 1) & 7)) << 4)); fa[4 + ks] = *(const LAS bf16x8*)(B + CH_AM + i1 * 128 + (((2 * ks + hi) ^ ((i1 >> 1) & 7)) << 4)); }
;             __builtin_amdgcn_sched_barrier(0);
;             MM_QD(fb, 4);
;             DECAY(2); DECAY(3);
;             __builtin_amdgcn_sched_barrier(0);
.LBB0_409:
	s_mul_i32 s92, s92, 0x12400
	s_add_i32 s22, s92, 0
	v_add_u32_e32 v74, s22, v205
	v_add_u32_e32 v75, s22, v141
	v_add_u32_e32 v66, v74, v149
	v_add_u32_e32 v70, v75, v149
	v_add_u32_e32 v76, v74, v151
	ds_read_b128 v[66:69], v66
	ds_read_b128 v[70:73], v70
	v_add_u32_e32 v77, v75, v151
	ds_read_b128 v[182:185], v76
	ds_read_b128 v[186:189], v77
	v_add_u32_e32 v76, v74, v153
	v_add_u32_e32 v77, v75, v153
	ds_read_b128 v[190:193], v76
	ds_read_b128 v[194:197], v77
	v_add_u32_e32 v76, v74, v160
	v_add_u32_e32 v77, v75, v160
	ds_read_b128 v[198:201], v76
	ds_read_b128 v[208:211], v77
	v_add_u32_e32 v76, s22, v173
	v_add_u32_e32 v77, v76, v162
	v_add_u32_e32 v78, v76, v164
	ds_read_b128 v[110:113], v77 offset:40960
	ds_read_b128 v[106:109], v78 offset:40960
	v_add_u32_e32 v77, v76, v165
	v_add_u32_e32 v76, v76, v166
	ds_read_b128 v[102:105], v77 offset:40960
	ds_read_b128 v[98:101], v76 offset:40960
	v_add_u32_e32 v76, v74, v167
	v_add_u32_e32 v77, v75, v167
	ds_read_b128 v[212:215], v76
	ds_read_b128 v[216:219], v77
	v_add_u32_e32 v76, v74, v168
	v_add_u32_e32 v77, v75, v168
	ds_read_b128 v[220:223], v76
	ds_read_b128 v[130:133], v77
	v_add_u32_e32 v76, v74, v169
	v_add_u32_e32 v74, v74, v170
	v_add_u32_e32 v77, v75, v169
	ds_read_b128 v[126:129], v76
	ds_read_b128 v[122:125], v77
	v_add_u32_e32 v75, v75, v170
	ds_read_b128 v[118:121], v74
	ds_read_b128 v[114:117], v75
	v_cvt_pk_bf16_f32 v74, v2, v3
	v_cvt_pk_bf16_f32 v75, v4, v5
	v_cvt_pk_bf16_f32 v76, v6, v7
	v_cvt_pk_bf16_f32 v77, v8, v9
	v_cvt_pk_bf16_f32 v224, v10, v11
	v_cvt_pk_bf16_f32 v225, v12, v13
	s_waitcnt lgkmcnt(0)
	v_mfma_f32_32x32x16_bf16 v[82:97], v[66:69], v[74:77], 0
	s_cmp_lt_i32 s8, 1
	s_cbranch_scc1 .Lvt_e_0
	s_and_b64 s[66:67], s[10:11], exec
	s_mov_b32 s65, 0x20000
	s_cselect_b32 s65, s65, 0xfffe0000
	s_ashr_i32 s95, s65, 31
	s_add_u32 s66, s68, s65
	s_addc_u32 s67, s69, s95
	s_lshl_b32 s65, s31, 4
	s_add_u32 s66, s66, s65
	s_addc_u32 s67, s67, 0
	s_add_i32 s95, s92, s65
	s_add_i32 m0, s95, 0xa000
	s_nop 0
	global_load_lds_dwordx4 v134, s[66:67] nt
	global_load_lds_dwordx4 v134, s[66:67] offset:1024 nt
	global_load_lds_dwordx4 v134, s[66:67] offset:2048 nt
	global_load_lds_dwordx4 v134, s[66:67] offset:3072 nt
.Lvt_e_0:
	v_cvt_pk_bf16_f32 v226, v14, v15
	v_cvt_pk_bf16_f32 v227, v16, v17
	v_add_u32_e32 v207, s22, v146
	v_add_u32_e32 v231, 0x12000, v207
	v_cvt_pk_bf16_f32 v228, v26, v27
	v_cvt_pk_bf16_f32 v229, v28, v29
	v_cvt_pk_bf16_f32 v230, v30, v31
	v_mfma_f32_32x32x16_bf16 v[66:81], v[70:73], v[74:77], 0
	v_mfma_f32_32x32x16_bf16 v[82:97], v[182:185], v[224:227], v[82:97]
	v_cvt_pk_bf16_f32 v182, v18, v19
	v_cvt_pk_bf16_f32 v183, v20, v21
	v_cvt_pk_bf16_f32 v184, v22, v23
	v_cvt_pk_bf16_f32 v185, v24, v25
	v_mfma_f32_32x32x16_bf16 v[66:81], v[186:189], v[224:227], v[66:81]
	ds_read_b128 v[186:189], v231 offset:64
	ds_read_b128 v[224:227], v231 offset:96
	ds_read_b128 v[232:235], v231
	ds_read_b128 v[236:239], v231 offset:32
	v_cvt_pk_bf16_f32 v231, v32, v33
	s_waitcnt lgkmcnt(0)
	v_pk_mul_f32 v[10:11], v[10:11], v[186:187]
	v_pk_mul_f32 v[12:13], v[12:13], v[188:189]
	v_pk_mul_f32 v[14:15], v[14:15], v[224:225]
	v_pk_mul_f32 v[6:7], v[6:7], v[236:237]
	v_pk_mul_f32 v[16:17], v[16:17], v[226:227]
	v_mfma_f32_32x32x16_bf16 v[82:97], v[190:193], v[182:185], v[82:97]
	v_mul_f32_e64 v8, v8, v238
	v_mul_f32_e64 v9, v9, v239
	v_mul_f32_e64 v4, v4, v234
	v_mul_f32_e64 v5, v5, v235
	v_mul_f32_e64 v2, v2, v232
	v_mul_f32_e64 v3, v3, v233
	v_mfma_f32_32x32x16_bf16 v[66:81], v[194:197], v[182:185], v[66:81]
	v_add_u32_e32 v194, 0x12080, v207
	ds_read_b128 v[182:185], v194 offset:64
	ds_read_b128 v[186:189], v194 offset:96
	ds_read_b128 v[190:193], v194
	ds_read_b128 v[194:197], v194 offset:32
	s_waitcnt lgkmcnt(0)
	v_pk_mul_f32 v[26:27], v[26:27], v[182:183]
	v_pk_mul_f32 v[30:31], v[30:31], v[186:187]
	v_pk_mul_f32 v[32:33], v[32:33], v[188:189]
	v_pk_mul_f32 v[22:23], v[22:23], v[194:195]
	v_pk_mul_f32 v[28:29], v[28:29], v[184:185]
	v_pk_mul_f32 v[24:25], v[24:25], v[196:197]
	v_pk_mul_f32 v[20:21], v[20:21], v[192:193]
	v_pk_mul_f32 v[18:19], v[18:19], v[190:191]
	v_mfma_f32_32x32x16_bf16 v[82:97], v[198:201], v[228:231], v[82:97]
	v_mfma_f32_32x32x16_bf16 v[66:81], v[208:211], v[228:231], v[66:81]
	v_add_u32_e32 v224, s22, v143
	v_add_u32_e32 v225, s22, v145
	v_add_u32_e32 v240, v224, v162
	v_add_u32_e32 v186, v225, v162
	v_add_u32_e32 v241, v224, v164
	v_add_u32_e32 v194, v225, v164
	v_add_u32_e32 v242, v224, v165
	v_add_u32_e32 v208, v225, v165
	v_add_u32_e32 v243, v224, v166
	v_add_u32_e32 v228, v225, v166
	ds_read_b128 v[182:185], v240 offset:16384
	ds_read_b128 v[186:189], v186 offset:16384
	ds_read_b128 v[190:193], v241 offset:16384
	ds_read_b128 v[194:197], v194 offset:16384
	ds_read_b128 v[198:201], v242 offset:16384
	ds_read_b128 v[208:211], v208 offset:16384
	ds_read_b128 v[224:227], v243 offset:16384
	ds_read_b128 v[228:231], v228 offset:16384
	v_cvt_pk_bf16_f32 v232, v34, v35
	v_cvt_pk_bf16_f32 v233, v36, v37
	v_cvt_pk_bf16_f32 v234, v38, v39
	v_cvt_pk_bf16_f32 v235, v40, v41
	s_nop 1
	v_mfma_f32_32x32x16_bf16 v[82:97], v[212:215], v[232:235], v[82:97]
	v_cvt_pk_bf16_f32 v212, v42, v43
	v_cvt_pk_bf16_f32 v213, v44, v45
	v_cvt_pk_bf16_f32 v214, v46, v47
	v_cvt_pk_bf16_f32 v215, v48, v49
	v_mfma_f32_32x32x16_bf16 v[66:81], v[216:219], v[232:235], v[66:81]
	v_cvt_pk_bf16_f32 v216, v50, v51
	v_cvt_pk_bf16_f32 v217, v52, v53
	v_cvt_pk_bf16_f32 v218, v54, v55
	v_cvt_pk_bf16_f32 v219, v56, v57
	v_mfma_f32_32x32x16_bf16 v[82:97], v[220:223], v[212:215], v[82:97]
	v_add_u32_e32 v223, 0x12100, v207
	v_add_u32_e32 v207, 0x12180, v207
	v_cvt_pk_bf16_f32 v220, v58, v59
	v_cvt_pk_bf16_f32 v221, v60, v61
	v_cvt_pk_bf16_f32 v222, v62, v63
	v_mfma_f32_32x32x16_bf16 v[66:81], v[130:133], v[212:215], v[66:81]
	ds_read_b128 v[130:133], v223 offset:64
	ds_read_b128 v[212:215], v223 offset:96
	ds_read_b128 v[232:235], v223
	ds_read_b128 v[236:239], v223 offset:32
	v_cvt_pk_bf16_f32 v223, v64, v65
	s_waitcnt lgkmcnt(0)
; #define LAS __attribute__((address_space(3)))
; DI int crow(int r, int hi) { return (r & 3) + 8 * (r >> 2) + 4 * hi; }
; DI unsigned pkbf(float a, float b) { f32x2 v = {a, b}; bfx2 r = __builtin_convertvector(v, bfx2); return __builtin_bit_cast(unsigned, r); }
; #define MM_KT(src, db0) _Pragma("unroll") for (int q_ = 0; q_ < 2; ++q_) { \
;                 _Pragma("unroll") for (int ks_ = 0; ks_ < 4; ++ks_) T[(db0) + q_] = __builtin_amdgcn_mfma_f32_32x32x16_bf16(src[q_ * 4 + ks_], vf[ks_], T[(db0) + q_], 0, 0, 0); }
; DI void phase_gla_chain(const Params& P, int l, int task0, int ntask_stride, LAS unsigned char* lds) {
;     ...
;             for (int ks = 0; ks < 4; ++ks) { fa[ks] = *(const LAS bf16x8*)(B + CH_AM + i0 * 128 + (((2 * ks + hi) ^ ((i0 >> 1) & 7)) << 4)); fa[4 + ks] = *(const LAS bf16x8*)(B + CH_AM + i1 * 128 + (((2 * ks + hi) ^ ((i1 >> 1) & 7)) << 4)); }
;             __builtin_amdgcn_sched_barrier(0);
;             MM_QD(fb, 4);
;             DECAY(2); DECAY(3);
;             __builtin_amdgcn_sched_barrier(0);
;             RD_KT(fb, 0);
;             __builtin_amdgcn_sched_barrier(0);
; #pragma unroll
;             for (int ks = 0; ks < 4; ++ks) { o[0] = __builtin_amdgcn_mfma_f32_32x32x16_bf16(fa[ks], vf[ks], o[0], 0, 0, 0); o[1] = __builtin_amdgcn_mfma_f32_32x32x16_bf16(fa[4 + ks], vf[ks], o[1], 0, 0, 0); }
;             __builtin_amdgcn_sched_barrier(0);
;             RD_KT(fa, 2);
;             __builtin_amdgcn_sched_barrier(0);
;             MM_KT(fb, 0);
;             __builtin_amdgcn_sched_barrier(0);
;             MM_KT(fa, 2);
;     ...
;             { const int cs = dir ? 63 - n : n; const size_t tokb = (size_t)sq * SEQL + cs * 64; const int odd = lane & 1;
;               bf16_t* ob = OFB + (size_t)dir * MTOK * 1024 + h * 256 + wid * 32 + (r32 & ~1);
; #pragma unroll
;               for (int ib = 0; ib < 2; ++ib)
; #pragma unroll
;                   for (int x = 0; x < 16; x += 2) { float ea_ = o[ib][x], eb_ = o[ib][x + 1]; asm volatile("" : "+v"(ea_), "+v"(eb_)); const float mine = odd ? eb_ : ea_, give = odd ? ea_ : eb_;
;                       const float got = __int_as_float(__builtin_amdgcn_update_dpp(0, __float_as_int(give), 0xB1, 0xF, 0xF, true));
;                       const unsigned w = odd ? pkbf(got, mine) : pkbf(mine, got);
;                       *(unsigned*)(ob + (tokb + ib * 32 + crow(x + odd, hi)) * 1024) = w; } }
	v_pk_mul_f32 v[42:43], v[42:43], v[130:131]
	v_pk_mul_f32 v[46:47], v[46:47], v[212:213]
	v_pk_mul_f32 v[48:49], v[48:49], v[214:215]
	v_pk_mul_f32 v[44:45], v[44:45], v[132:133]
	v_pk_mul_f32 v[38:39], v[38:39], v[236:237]
	v_mfma_f32_32x32x16_bf16 v[82:97], v[126:129], v[216:219], v[82:97]
	v_mul_f32_e64 v40, v40, v238
	v_mul_f32_e64 v41, v41, v239
	v_mul_f32_e64 v36, v36, v234
	v_mul_f32_e64 v37, v37, v235
	v_mul_f32_e64 v34, v34, v232
	v_mul_f32_e64 v35, v35, v233
	v_mfma_f32_32x32x16_bf16 v[66:81], v[122:125], v[216:219], v[66:81]
	ds_read_b128 v[122:125], v207 offset:64
	ds_read_b128 v[126:129], v207 offset:96
	ds_read_b128 v[130:133], v207
	ds_read_b128 v[212:215], v207 offset:32
	s_waitcnt lgkmcnt(0)
	v_pk_mul_f32 v[58:59], v[58:59], v[122:123]
	v_pk_mul_f32 v[62:63], v[62:63], v[126:127]
	v_pk_mul_f32 v[64:65], v[64:65], v[128:129]
	v_pk_mul_f32 v[54:55], v[54:55], v[212:213]
	v_pk_mul_f32 v[60:61], v[60:61], v[124:125]
	v_pk_mul_f32 v[56:57], v[56:57], v[214:215]
	v_pk_mul_f32 v[52:53], v[52:53], v[132:133]
	v_pk_mul_f32 v[50:51], v[50:51], v[130:131]
	v_mfma_f32_32x32x16_bf16 v[82:97], v[118:121], v[220:223], v[82:97]
	v_mfma_f32_32x32x16_bf16 v[66:81], v[114:117], v[220:223], v[66:81]
	ds_read_b128 v[114:117], v240 offset:24576
	ds_read_b128 v[118:121], v240 offset:28672
	ds_read_b128 v[122:125], v241 offset:24576
	ds_read_b128 v[126:129], v241 offset:28672
	ds_read_b128 v[130:133], v242 offset:24576
	ds_read_b128 v[212:215], v242 offset:28672
	ds_read_b128 v[216:219], v243 offset:24576
	ds_read_b128 v[220:223], v243 offset:28672
	v_mfma_f32_32x32x16_bf16 v[82:97], v[182:185], v[110:113], v[82:97]
	v_mfma_f32_32x32x16_bf16 v[66:81], v[186:189], v[110:113], v[66:81]
	v_mfma_f32_32x32x16_bf16 v[82:97], v[190:193], v[106:109], v[82:97]
	v_mfma_f32_32x32x16_bf16 v[66:81], v[194:197], v[106:109], v[66:81]
	v_mfma_f32_32x32x16_bf16 v[82:97], v[198:201], v[102:105], v[82:97]
	v_mfma_f32_32x32x16_bf16 v[66:81], v[208:211], v[102:105], v[66:81]
	v_mfma_f32_32x32x16_bf16 v[82:97], v[224:227], v[98:101], v[82:97]
	v_mfma_f32_32x32x16_bf16 v[66:81], v[228:231], v[98:101], v[66:81]
	ds_read_b128 v[182:185], v240 offset:32768
	ds_read_b128 v[186:189], v240 offset:36864
	ds_read_b128 v[190:193], v241 offset:32768
	ds_read_b128 v[194:197], v241 offset:36864
	ds_read_b128 v[198:201], v242 offset:32768
	ds_read_b128 v[208:211], v242 offset:36864
	ds_read_b128 v[224:227], v243 offset:32768
	ds_read_b128 v[228:231], v243 offset:36864
	s_waitcnt lgkmcnt(0)
	v_mfma_f32_32x32x16_bf16 v[2:17], v[114:117], v[110:113], v[2:17]
	v_mfma_f32_32x32x16_bf16 v[18:33], v[118:121], v[110:113], v[18:33]
	v_mfma_f32_32x32x16_bf16 v[2:17], v[122:125], v[106:109], v[2:17]
	v_mfma_f32_32x32x16_bf16 v[18:33], v[126:129], v[106:109], v[18:33]
	v_mfma_f32_32x32x16_bf16 v[2:17], v[130:133], v[102:105], v[2:17]
	v_mfma_f32_32x32x16_bf16 v[18:33], v[212:215], v[102:105], v[18:33]
	v_mfma_f32_32x32x16_bf16 v[2:17], v[216:219], v[98:101], v[2:17]
	v_mfma_f32_32x32x16_bf16 v[18:33], v[220:223], v[98:101], v[18:33]
	s_add_i32 s64, s8, 1
	s_and_b64 s[22:23], s[10:11], exec
	s_cselect_b32 s22, s91, s64
	s_lshl_b32 s22, s22, 6
	s_add_u32 s23, s20, s22
	v_cndmask_b32_e64 v114, v82, v83, s[0:1]
	s_addc_u32 s22, s21, 0
	v_mfma_f32_32x32x16_bf16 v[34:49], v[182:185], v[110:113], v[34:49]
	v_mov_b32_dpp v114, v114 quad_perm:[1,0,3,2] row_mask:0xf bank_mask:0xf bound_ctrl:1
	v_cndmask_b32_e64 v83, v83, v114, s[0:1]
	v_cndmask_b32_e64 v82, v114, v82, s[0:1]
	v_cvt_pk_bf16_f32 v114, v82, v83
	v_readfirstlane_b32 s98, v158
	v_readfirstlane_b32 s99, v159
	v_and_b32_e32 v244, 30, v137
	v_lshlrev_b32_e32 v244, 1, v244
	v_lshl_add_u32 v244, v136, 11, v244
	s_lshl_b32 s100, s23, 11
	s_add_u32 s98, s98, s100
	s_addc_u32 s99, s99, 0
	s_add_u32 s100, s98, 0x800
	s_addc_u32 s101, s99, 0
	global_store_dword v244, v114, s[100:101] offset:-2048
	v_mov_b32_e32 v82, v84
	v_mfma_f32_32x32x16_bf16 v[50:65], v[186:189], v[110:113], v[50:65]
	v_cndmask_b32_e64 v83, v82, v85, s[0:1]
	s_add_i32 s8, s8, -1
	s_add_i32 s90, s90, 1
	v_mov_b32_dpp v83, v83 quad_perm:[1,0,3,2] row_mask:0xf bank_mask:0xf bound_ctrl:1
	v_cndmask_b32_e64 v84, v85, v83, s[0:1]
	v_cndmask_b32_e64 v82, v83, v82, s[0:1]
	v_cvt_pk_bf16_f32 v84, v82, v84
	global_store_dword v244, v84, s[100:101] offset:2048
	v_mov_b32_e32 v82, v87
	v_mfma_f32_32x32x16_bf16 v[34:49], v[190:193], v[106:109], v[34:49]
	v_cndmask_b32_e64 v83, v86, v82, s[0:1]
	s_nop 1
	v_mov_b32_dpp v83, v83 quad_perm:[1,0,3,2] row_mask:0xf bank_mask:0xf bound_ctrl:1
	v_cndmask_b32_e64 v82, v82, v83, s[0:1]
	v_cndmask_b32_e64 v83, v83, v86, s[0:1]
	v_cvt_pk_bf16_f32 v84, v83, v82
	s_add_u32 s100, s98, 0x4800
	s_addc_u32 s101, s99, 0
	global_store_dword v244, v84, s[100:101] offset:-2048
	v_mov_b32_e32 v82, v88
	v_mfma_f32_32x32x16_bf16 v[50:65], v[194:197], v[106:109], v[50:65]
	v_cndmask_b32_e64 v83, v82, v89, s[0:1]
	s_nop 1
; DI int crow(int r, int hi) { return (r & 3) + 8 * (r >> 2) + 4 * hi; }
; DI unsigned pkbf(float a, float b) { f32x2 v = {a, b}; bfx2 r = __builtin_convertvector(v, bfx2); return __builtin_bit_cast(unsigned, r); }
; DI void phase_gla_chain(const Params& P, int l, int task0, int ntask_stride, LAS unsigned char* lds) {
;     ...
;             { const int cs = dir ? 63 - n : n; const size_t tokb = (size_t)sq * SEQL + cs * 64; const int odd = lane & 1;
;               bf16_t* ob = OFB + (size_t)dir * MTOK * 1024 + h * 256 + wid * 32 + (r32 & ~1);
; #pragma unroll
;               for (int ib = 0; ib < 2; ++ib)
; #pragma unroll
;                   for (int x = 0; x < 16; x += 2) { float ea_ = o[ib][x], eb_ = o[ib][x + 1]; asm volatile("" : "+v"(ea_), "+v"(eb_)); const float mine = odd ? eb_ : ea_, give = odd ? ea_ : eb_;
;                       const float got = __int_as_float(__builtin_amdgcn_update_dpp(0, __float_as_int(give), 0xB1, 0xF, 0xF, true));
;                       const unsigned w = odd ? pkbf(got, mine) : pkbf(mine, got);
;                       *(unsigned*)(ob + (tokb + ib * 32 + crow(x + odd, hi)) * 1024) = w; } }
	v_mov_b32_dpp v83, v83 quad_perm:[1,0,3,2] row_mask:0xf bank_mask:0xf bound_ctrl:1
	v_cndmask_b32_e64 v84, v89, v83, s[0:1]
	v_cndmask_b32_e64 v82, v83, v82, s[0:1]
	v_cvt_pk_bf16_f32 v84, v82, v84
	global_store_dword v244, v84, s[100:101] offset:2048
	v_mov_b32_e32 v82, v90
	v_mfma_f32_32x32x16_bf16 v[34:49], v[198:201], v[102:105], v[34:49]
	v_cndmask_b32_e64 v83, v82, v91, s[0:1]
	s_nop 1
	v_mov_b32_dpp v83, v83 quad_perm:[1,0,3,2] row_mask:0xf bank_mask:0xf bound_ctrl:1
	v_cndmask_b32_e64 v84, v91, v83, s[0:1]
	v_cndmask_b32_e64 v82, v83, v82, s[0:1]
	v_cvt_pk_bf16_f32 v84, v82, v84
	s_add_u32 s100, s98, 0x8800
	s_addc_u32 s101, s99, 0
	global_store_dword v244, v84, s[100:101] offset:-2048
	v_mov_b32_e32 v82, v93
	v_mfma_f32_32x32x16_bf16 v[50:65], v[208:211], v[102:105], v[50:65]
	v_cndmask_b32_e64 v83, v92, v82, s[0:1]
	s_nop 1
	v_mov_b32_dpp v83, v83 quad_perm:[1,0,3,2] row_mask:0xf bank_mask:0xf bound_ctrl:1
	v_cndmask_b32_e64 v82, v82, v83, s[0:1]
	v_cndmask_b32_e64 v83, v83, v92, s[0:1]
	v_cvt_pk_bf16_f32 v84, v83, v82
	global_store_dword v244, v84, s[100:101] offset:2048
	v_mov_b32_e32 v82, v94
	v_mfma_f32_32x32x16_bf16 v[34:49], v[224:227], v[98:101], v[34:49]
	v_cndmask_b32_e64 v83, v82, v95, s[0:1]
	s_nop 1
	v_mov_b32_dpp v83, v83 quad_perm:[1,0,3,2] row_mask:0xf bank_mask:0xf bound_ctrl:1
	v_cndmask_b32_e64 v84, v95, v83, s[0:1]
	v_cndmask_b32_e64 v82, v83, v82, s[0:1]
	v_cvt_pk_bf16_f32 v84, v82, v84
	s_add_u32 s100, s98, 0xc800
	s_addc_u32 s101, s99, 0
	global_store_dword v244, v84, s[100:101] offset:-2048
	v_mov_b32_e32 v82, v96
	v_mfma_f32_32x32x16_bf16 v[50:65], v[228:231], v[98:101], v[50:65]
	v_cndmask_b32_e64 v83, v82, v97, s[0:1]
	s_nop 1
	v_mov_b32_dpp v83, v83 quad_perm:[1,0,3,2] row_mask:0xf bank_mask:0xf bound_ctrl:1
	v_cndmask_b32_e64 v84, v97, v83, s[0:1]
	v_cndmask_b32_e64 v82, v83, v82, s[0:1]
	v_cvt_pk_bf16_f32 v84, v82, v84
	global_store_dword v244, v84, s[100:101] offset:2048
	s_or_b32 s23, s23, 32
	v_cndmask_b32_e64 v82, v66, v67, s[0:1]
	s_nop 0
	v_mov_b32_dpp v82, v82 quad_perm:[1,0,3,2] row_mask:0xf bank_mask:0xf bound_ctrl:1
	v_cndmask_b32_e64 v67, v67, v82, s[0:1]
	v_cndmask_b32_e64 v66, v82, v66, s[0:1]
	v_cvt_pk_bf16_f32 v82, v66, v67
	s_add_u32 s100, s98, 0x10800
	s_addc_u32 s101, s99, 0
	global_store_dword v244, v82, s[100:101] offset:-2048
	v_mov_b32_e32 v66, v68
	s_nop 0
	v_cndmask_b32_e64 v67, v66, v69, s[0:1]
	s_nop 1
	v_mov_b32_dpp v67, v67 quad_perm:[1,0,3,2] row_mask:0xf bank_mask:0xf bound_ctrl:1
	v_cndmask_b32_e64 v68, v69, v67, s[0:1]
	v_cndmask_b32_e64 v66, v67, v66, s[0:1]
	v_cvt_pk_bf16_f32 v68, v66, v68
	global_store_dword v244, v68, s[100:101] offset:2048
	v_mov_b32_e32 v66, v70
	s_nop 0
	v_cndmask_b32_e64 v67, v66, v71, s[0:1]
	s_nop 1
	v_mov_b32_dpp v67, v67 quad_perm:[1,0,3,2] row_mask:0xf bank_mask:0xf bound_ctrl:1
	v_cndmask_b32_e64 v68, v71, v67, s[0:1]
	v_cndmask_b32_e64 v66, v67, v66, s[0:1]
	v_cvt_pk_bf16_f32 v68, v66, v68
	s_add_u32 s100, s98, 0x14800
	s_addc_u32 s101, s99, 0
	global_store_dword v244, v68, s[100:101] offset:-2048
	v_mov_b32_e32 v66, v73
	s_nop 0
	v_cndmask_b32_e64 v67, v72, v66, s[0:1]
	s_nop 1
	v_mov_b32_dpp v67, v67 quad_perm:[1,0,3,2] row_mask:0xf bank_mask:0xf bound_ctrl:1
	v_cndmask_b32_e64 v66, v66, v67, s[0:1]
	v_cndmask_b32_e64 v67, v67, v72, s[0:1]
	v_cvt_pk_bf16_f32 v68, v67, v66
	global_store_dword v244, v68, s[100:101] offset:2048
	v_mov_b32_e32 v66, v74
	s_nop 0
	v_cndmask_b32_e64 v67, v66, v75, s[0:1]
	s_nop 1
	v_mov_b32_dpp v67, v67 quad_perm:[1,0,3,2] row_mask:0xf bank_mask:0xf bound_ctrl:1
	v_cndmask_b32_e64 v68, v75, v67, s[0:1]
	v_cndmask_b32_e64 v66, v67, v66, s[0:1]
	v_cvt_pk_bf16_f32 v68, v66, v68
	s_add_u32 s100, s98, 0x18800
	s_addc_u32 s101, s99, 0
	global_store_dword v244, v68, s[100:101] offset:-2048
	v_mov_b32_e32 v66, v76
	s_nop 0
	v_cndmask_b32_e64 v67, v66, v77, s[0:1]
	s_nop 1
	v_mov_b32_dpp v67, v67 quad_perm:[1,0,3,2] row_mask:0xf bank_mask:0xf bound_ctrl:1
	v_cndmask_b32_e64 v68, v77, v67, s[0:1]
	v_cndmask_b32_e64 v66, v67, v66, s[0:1]
	v_cvt_pk_bf16_f32 v68, v66, v68
	global_store_dword v244, v68, s[100:101] offset:2048
	v_mov_b32_e32 v66, v79
	s_nop 0
	v_cndmask_b32_e64 v67, v78, v66, s[0:1]
	s_nop 1
	v_mov_b32_dpp v67, v67 quad_perm:[1,0,3,2] row_mask:0xf bank_mask:0xf bound_ctrl:1
	v_cndmask_b32_e64 v66, v66, v67, s[0:1]
	v_cndmask_b32_e64 v67, v67, v78, s[0:1]
	v_cvt_pk_bf16_f32 v68, v67, v66
	s_add_u32 s100, s98, 0x1c800
	s_addc_u32 s101, s99, 0
	global_store_dword v244, v68, s[100:101] offset:-2048
	v_mov_b32_e32 v66, v81
	s_nop 0
	v_cndmask_b32_e64 v67, v80, v66, s[0:1]
	s_nop 1
	v_mov_b32_dpp v67, v67 quad_perm:[1,0,3,2] row_mask:0xf bank_mask:0xf bound_ctrl:1
	v_cndmask_b32_e64 v66, v66, v67, s[0:1]
	v_cndmask_b32_e64 v67, v67, v80, s[0:1]
	v_cvt_pk_bf16_f32 v68, v67, v66
	global_store_dword v244, v68, s[100:101] offset:2048
	s_cmp_eq_u32 s8, -2
	s_cbranch_scc1 .LBB0_403

; #define LAS __attribute__((address_space(3)))
; #define RD_QD(dst, s0) _Pragma("unroll") for (int s_ = 0; s_ < 4; ++s_) { dst[s_] = *(const LAS bf16x8*)(B + CH_QD + i0 * 256 + (((2 * ((s0) + s_) + hi) ^ (i0 & 15)) << 4)); \
;                 dst[4 + s_] = *(const LAS bf16x8*)(B + CH_QD + i1 * 256 + (((2 * ((s0) + s_) + hi) ^ (i1 & 15)) << 4)); }
; #define DECAY(db_) do { f32x4 dc_[4]; _Pragma("unroll") for (int a4_ = 0; a4_ < 4; ++a4_) dc_[a4_] = *(const LAS f32x4*)(B + CH_DEC + ((db_) * 32 + 8 * a4_ + 4 * hi) * 4); \
;                 _Pragma("unroll") for (int a4_ = 0; a4_ < 4; ++a4_) _Pragma("unroll") for (int b4_ = 0; b4_ < 4; ++b4_) T[db_][a4_ * 4 + b4_] *= dc_[a4_][b4_]; } while (0)
; DI void phase_gla_chain(const Params& P, int l, int task0, int ntask_stride, LAS unsigned char* lds) {
;     ...
;             const int i0 = r32, i1 = 32 + r32; const int vv = wid * 32 + r32;
;             bf16x8 fa[8], fb[8], vf[4];
;             f32x16 o[2]; for (int x = 0; x < 16; ++x) { o[0][x] = 0.f; o[1][x] = 0.f; }
;     ...
;             RD_QD(fa, 0);
; #pragma unroll
;             for (int ks = 0; ks < 4; ++ks) vf[ks] = *(const LAS bf16x8*)(B + CH_VT + vv * 128 + (((2 * ks + hi) ^ ((vv >> 1) & 7)) << 4));
;             __builtin_amdgcn_sched_barrier(0);
;             RD_QD(fb, 4);
;             __builtin_amdgcn_sched_barrier(0);
;             MM_QD(fa, 0);
;             DECAY(0); DECAY(1);
;             __builtin_amdgcn_sched_barrier(0);
; #pragma unroll
;             for (int ks = 0; ks < 4; ++ks) { fa[ks] = *(const LAS bf16x8*)(B + CH_AM + i0 * 128 + (((2 * ks + hi) ^ ((i0 >> 1) & 7)) << 4)); fa[4 + ks] = *(const LAS bf16x8*)(B + CH_AM + i1 * 128 + (((2 * ks + hi) ^ ((i1 >> 1) & 7)) << 4)); }
;             __builtin_amdgcn_sched_barrier(0);
;             MM_QD(fb, 4);
;             DECAY(2); DECAY(3);
;             __builtin_amdgcn_sched_barrier(0);
.LBB0_971:
	s_mul_i32 s84, s84, 0x12400
	s_add_i32 s22, s84, 0
	v_add_u32_e32 v74, s22, v201
	v_add_u32_e32 v75, s22, v141
	v_add_u32_e32 v66, v74, v149
	v_add_u32_e32 v70, v75, v149
	v_add_u32_e32 v76, v74, v151
	ds_read_b128 v[66:69], v66
	ds_read_b128 v[70:73], v70
	v_add_u32_e32 v77, v75, v151
	ds_read_b128 v[182:185], v76
	ds_read_b128 v[186:189], v77
	v_add_u32_e32 v76, v74, v153
	v_add_u32_e32 v77, v75, v153
	ds_read_b128 v[190:193], v76
	ds_read_b128 v[194:197], v77
	v_add_u32_e32 v76, v74, v160
	v_add_u32_e32 v77, v75, v160
	ds_read_b128 v[204:207], v76
	ds_read_b128 v[208:211], v77
	v_add_u32_e32 v76, s22, v173
	v_add_u32_e32 v77, v76, v162
	v_add_u32_e32 v78, v76, v164
	ds_read_b128 v[110:113], v77 offset:40960
	ds_read_b128 v[106:109], v78 offset:40960
	v_add_u32_e32 v77, v76, v165
	v_add_u32_e32 v76, v76, v166
	ds_read_b128 v[102:105], v77 offset:40960
	ds_read_b128 v[98:101], v76 offset:40960
	v_add_u32_e32 v76, v74, v167
	v_add_u32_e32 v77, v75, v167
	ds_read_b128 v[212:215], v76
	ds_read_b128 v[216:219], v77
	v_add_u32_e32 v76, v74, v168
	v_add_u32_e32 v77, v75, v168
	ds_read_b128 v[220:223], v76
	ds_read_b128 v[130:133], v77
	v_add_u32_e32 v76, v74, v169
	v_add_u32_e32 v74, v74, v170
	v_add_u32_e32 v77, v75, v169
	ds_read_b128 v[126:129], v76
	ds_read_b128 v[122:125], v77
	v_add_u32_e32 v75, v75, v170
	ds_read_b128 v[118:121], v74
	ds_read_b128 v[114:117], v75
	v_cvt_pk_bf16_f32 v74, v2, v3
	v_cvt_pk_bf16_f32 v75, v4, v5
	v_cvt_pk_bf16_f32 v76, v6, v7
	v_cvt_pk_bf16_f32 v77, v8, v9
	v_cvt_pk_bf16_f32 v224, v10, v11
	v_cvt_pk_bf16_f32 v225, v12, v13
	s_waitcnt lgkmcnt(0)
	v_mfma_f32_32x32x16_bf16 v[82:97], v[66:69], v[74:77], 0
	s_cmp_lt_i32 s8, 1
	s_cbranch_scc1 .Lvt_e_1
	s_and_b64 s[88:89], s[10:11], exec
	s_mov_b32 s90, 0x20000
	s_cselect_b32 s90, s90, 0xfffe0000
	s_ashr_i32 s91, s90, 31
	s_add_u32 s88, s66, s90
	s_addc_u32 s89, s67, s91
	s_lshl_b32 s90, s31, 4
	s_add_u32 s88, s88, s90
	s_addc_u32 s89, s89, 0
	s_add_i32 s91, s84, s90
	s_add_i32 m0, s91, 0xa000
	s_nop 0
	global_load_lds_dwordx4 v134, s[88:89] nt
	global_load_lds_dwordx4 v134, s[88:89] offset:1024 nt
	global_load_lds_dwordx4 v134, s[88:89] offset:2048 nt
	global_load_lds_dwordx4 v134, s[88:89] offset:3072 nt
.Lvt_e_1:
	v_cvt_pk_bf16_f32 v226, v14, v15
	v_cvt_pk_bf16_f32 v227, v16, v17
	v_add_u32_e32 v198, s22, v146
	v_add_u32_e32 v199, 0x12000, v198
	v_cvt_pk_bf16_f32 v228, v26, v27
	v_cvt_pk_bf16_f32 v229, v28, v29
	v_cvt_pk_bf16_f32 v230, v30, v31
	v_mfma_f32_32x32x16_bf16 v[66:81], v[70:73], v[74:77], 0
	v_cvt_pk_bf16_f32 v231, v32, v33
	v_mfma_f32_32x32x16_bf16 v[82:97], v[182:185], v[224:227], v[82:97]
	v_cvt_pk_bf16_f32 v182, v18, v19
	v_cvt_pk_bf16_f32 v183, v20, v21
	v_cvt_pk_bf16_f32 v184, v22, v23
	v_cvt_pk_bf16_f32 v185, v24, v25
	v_mfma_f32_32x32x16_bf16 v[66:81], v[186:189], v[224:227], v[66:81]
	ds_read_b128 v[186:189], v199 offset:64
	ds_read_b128 v[224:227], v199 offset:96
	ds_read_b128 v[232:235], v199
	ds_read_b128 v[236:239], v199 offset:32
	s_waitcnt lgkmcnt(0)
	v_pk_mul_f32 v[10:11], v[10:11], v[186:187]
	v_pk_mul_f32 v[12:13], v[12:13], v[188:189]
	v_pk_mul_f32 v[14:15], v[14:15], v[224:225]
	v_pk_mul_f32 v[6:7], v[6:7], v[236:237]
	v_pk_mul_f32 v[16:17], v[16:17], v[226:227]
	v_mfma_f32_32x32x16_bf16 v[82:97], v[190:193], v[182:185], v[82:97]
	v_mul_f32_e64 v8, v8, v238
	v_mul_f32_e64 v9, v9, v239
	v_mul_f32_e64 v4, v4, v234
	v_mul_f32_e64 v5, v5, v235
	v_mul_f32_e64 v2, v2, v232
	v_mul_f32_e64 v3, v3, v233
	v_mfma_f32_32x32x16_bf16 v[66:81], v[194:197], v[182:185], v[66:81]
	v_add_u32_e32 v194, 0x12080, v198
	ds_read_b128 v[182:185], v194 offset:64
	ds_read_b128 v[186:189], v194 offset:96
	ds_read_b128 v[190:193], v194
	ds_read_b128 v[194:197], v194 offset:32
	s_waitcnt lgkmcnt(0)
	v_pk_mul_f32 v[26:27], v[26:27], v[182:183]
	v_pk_mul_f32 v[30:31], v[30:31], v[186:187]
	v_pk_mul_f32 v[32:33], v[32:33], v[188:189]
	v_pk_mul_f32 v[22:23], v[22:23], v[194:195]
	v_pk_mul_f32 v[28:29], v[28:29], v[184:185]
	v_pk_mul_f32 v[24:25], v[24:25], v[196:197]
	v_pk_mul_f32 v[20:21], v[20:21], v[192:193]
	v_pk_mul_f32 v[18:19], v[18:19], v[190:191]
	v_mfma_f32_32x32x16_bf16 v[82:97], v[204:207], v[228:231], v[82:97]
	v_mfma_f32_32x32x16_bf16 v[66:81], v[208:211], v[228:231], v[66:81]
	v_add_u32_e32 v199, s22, v143
	v_add_u32_e32 v224, s22, v145
	v_add_u32_e32 v240, v199, v162
	v_add_u32_e32 v186, v224, v162
	v_add_u32_e32 v241, v199, v164
	v_add_u32_e32 v194, v224, v164
	v_add_u32_e32 v242, v199, v165
	v_add_u32_e32 v208, v224, v165
	v_add_u32_e32 v199, v199, v166
	v_add_u32_e32 v228, v224, v166
	ds_read_b128 v[182:185], v240 offset:16384
	ds_read_b128 v[186:189], v186 offset:16384
	ds_read_b128 v[190:193], v241 offset:16384
	ds_read_b128 v[194:197], v194 offset:16384
	ds_read_b128 v[204:207], v242 offset:16384
	ds_read_b128 v[208:211], v208 offset:16384
	ds_read_b128 v[224:227], v199 offset:16384
	ds_read_b128 v[228:231], v228 offset:16384
	v_cvt_pk_bf16_f32 v232, v34, v35
	v_cvt_pk_bf16_f32 v233, v36, v37
	v_cvt_pk_bf16_f32 v234, v38, v39
	v_cvt_pk_bf16_f32 v235, v40, v41
	s_nop 1
	v_mfma_f32_32x32x16_bf16 v[82:97], v[212:215], v[232:235], v[82:97]
	v_cvt_pk_bf16_f32 v212, v42, v43
	v_cvt_pk_bf16_f32 v213, v44, v45
	v_cvt_pk_bf16_f32 v214, v46, v47
	v_cvt_pk_bf16_f32 v215, v48, v49
	v_mfma_f32_32x32x16_bf16 v[66:81], v[216:219], v[232:235], v[66:81]
	v_cvt_pk_bf16_f32 v216, v50, v51
	v_cvt_pk_bf16_f32 v217, v52, v53
	v_cvt_pk_bf16_f32 v218, v54, v55
	v_cvt_pk_bf16_f32 v219, v56, v57
	v_mfma_f32_32x32x16_bf16 v[82:97], v[220:223], v[212:215], v[82:97]
	v_add_u32_e32 v223, 0x12100, v198
	v_add_u32_e32 v198, 0x12180, v198
	v_cvt_pk_bf16_f32 v220, v58, v59
	v_cvt_pk_bf16_f32 v221, v60, v61
	v_cvt_pk_bf16_f32 v222, v62, v63
	v_mfma_f32_32x32x16_bf16 v[66:81], v[130:133], v[212:215], v[66:81]
	ds_read_b128 v[130:133], v223 offset:64
	ds_read_b128 v[212:215], v223 offset:96
	ds_read_b128 v[232:235], v223
	ds_read_b128 v[236:239], v223 offset:32
	v_cvt_pk_bf16_f32 v223, v64, v65
	s_waitcnt lgkmcnt(0)
; #define LAS __attribute__((address_space(3)))
; DI int crow(int r, int hi) { return (r & 3) + 8 * (r >> 2) + 4 * hi; }
; DI unsigned pkbf(float a, float b) { f32x2 v = {a, b}; bfx2 r = __builtin_convertvector(v, bfx2); return __builtin_bit_cast(unsigned, r); }
; #define MM_KT(src, db0) _Pragma("unroll") for (int q_ = 0; q_ < 2; ++q_) { \
;                 _Pragma("unroll") for (int ks_ = 0; ks_ < 4; ++ks_) T[(db0) + q_] = __builtin_amdgcn_mfma_f32_32x32x16_bf16(src[q_ * 4 + ks_], vf[ks_], T[(db0) + q_], 0, 0, 0); }
; DI void phase_gla_chain(const Params& P, int l, int task0, int ntask_stride, LAS unsigned char* lds) {
;     ...
;             for (int ks = 0; ks < 4; ++ks) { fa[ks] = *(const LAS bf16x8*)(B + CH_AM + i0 * 128 + (((2 * ks + hi) ^ ((i0 >> 1) & 7)) << 4)); fa[4 + ks] = *(const LAS bf16x8*)(B + CH_AM + i1 * 128 + (((2 * ks + hi) ^ ((i1 >> 1) & 7)) << 4)); }
;             __builtin_amdgcn_sched_barrier(0);
;             MM_QD(fb, 4);
;             DECAY(2); DECAY(3);
;             __builtin_amdgcn_sched_barrier(0);
;             RD_KT(fb, 0);
;             __builtin_amdgcn_sched_barrier(0);
; #pragma unroll
;             for (int ks = 0; ks < 4; ++ks) { o[0] = __builtin_amdgcn_mfma_f32_32x32x16_bf16(fa[ks], vf[ks], o[0], 0, 0, 0); o[1] = __builtin_amdgcn_mfma_f32_32x32x16_bf16(fa[4 + ks], vf[ks], o[1], 0, 0, 0); }
;             __builtin_amdgcn_sched_barrier(0);
;             RD_KT(fa, 2);
;             __builtin_amdgcn_sched_barrier(0);
;             MM_KT(fb, 0);
;             __builtin_amdgcn_sched_barrier(0);
;             MM_KT(fa, 2);
;     ...
;             { const int cs = dir ? 63 - n : n; const size_t tokb = (size_t)sq * SEQL + cs * 64; const int odd = lane & 1;
;               bf16_t* ob = OFB + (size_t)dir * MTOK * 1024 + h * 256 + wid * 32 + (r32 & ~1);
; #pragma unroll
;               for (int ib = 0; ib < 2; ++ib)
; #pragma unroll
;                   for (int x = 0; x < 16; x += 2) { float ea_ = o[ib][x], eb_ = o[ib][x + 1]; asm volatile("" : "+v"(ea_), "+v"(eb_)); const float mine = odd ? eb_ : ea_, give = odd ? ea_ : eb_;
;                       const float got = __int_as_float(__builtin_amdgcn_update_dpp(0, __float_as_int(give), 0xB1, 0xF, 0xF, true));
;                       const unsigned w = odd ? pkbf(got, mine) : pkbf(mine, got);
;                       *(unsigned*)(ob + (tokb + ib * 32 + crow(x + odd, hi)) * 1024) = w; } }
	v_pk_mul_f32 v[42:43], v[42:43], v[130:131]
	v_pk_mul_f32 v[46:47], v[46:47], v[212:213]
	v_pk_mul_f32 v[48:49], v[48:49], v[214:215]
	v_pk_mul_f32 v[44:45], v[44:45], v[132:133]
	v_pk_mul_f32 v[38:39], v[38:39], v[236:237]
	v_mfma_f32_32x32x16_bf16 v[82:97], v[126:129], v[216:219], v[82:97]
	v_mul_f32_e64 v40, v40, v238
	v_mul_f32_e64 v41, v41, v239
	v_mul_f32_e64 v36, v36, v234
	v_mul_f32_e64 v37, v37, v235
	v_mul_f32_e64 v34, v34, v232
	v_mul_f32_e64 v35, v35, v233
	v_mfma_f32_32x32x16_bf16 v[66:81], v[122:125], v[216:219], v[66:81]
	ds_read_b128 v[122:125], v198 offset:64
	ds_read_b128 v[126:129], v198 offset:96
	ds_read_b128 v[130:133], v198
	ds_read_b128 v[212:215], v198 offset:32
	s_waitcnt lgkmcnt(0)
	v_pk_mul_f32 v[58:59], v[58:59], v[122:123]
	v_pk_mul_f32 v[62:63], v[62:63], v[126:127]
	v_pk_mul_f32 v[64:65], v[64:65], v[128:129]
	v_pk_mul_f32 v[54:55], v[54:55], v[212:213]
	v_pk_mul_f32 v[60:61], v[60:61], v[124:125]
	v_pk_mul_f32 v[56:57], v[56:57], v[214:215]
	v_pk_mul_f32 v[52:53], v[52:53], v[132:133]
	v_pk_mul_f32 v[50:51], v[50:51], v[130:131]
	v_mfma_f32_32x32x16_bf16 v[82:97], v[118:121], v[220:223], v[82:97]
	v_mfma_f32_32x32x16_bf16 v[66:81], v[114:117], v[220:223], v[66:81]
	ds_read_b128 v[114:117], v240 offset:24576
	ds_read_b128 v[118:121], v240 offset:28672
	ds_read_b128 v[122:125], v241 offset:24576
	ds_read_b128 v[126:129], v241 offset:28672
	ds_read_b128 v[130:133], v242 offset:24576
	ds_read_b128 v[212:215], v242 offset:28672
	ds_read_b128 v[216:219], v199 offset:24576
	ds_read_b128 v[220:223], v199 offset:28672
	v_mfma_f32_32x32x16_bf16 v[82:97], v[182:185], v[110:113], v[82:97]
	v_mfma_f32_32x32x16_bf16 v[66:81], v[186:189], v[110:113], v[66:81]
	v_mfma_f32_32x32x16_bf16 v[82:97], v[190:193], v[106:109], v[82:97]
	v_mfma_f32_32x32x16_bf16 v[66:81], v[194:197], v[106:109], v[66:81]
	v_mfma_f32_32x32x16_bf16 v[82:97], v[204:207], v[102:105], v[82:97]
	v_mfma_f32_32x32x16_bf16 v[66:81], v[208:211], v[102:105], v[66:81]
	v_mfma_f32_32x32x16_bf16 v[82:97], v[224:227], v[98:101], v[82:97]
	v_mfma_f32_32x32x16_bf16 v[66:81], v[228:231], v[98:101], v[66:81]
	ds_read_b128 v[182:185], v240 offset:32768
	ds_read_b128 v[186:189], v240 offset:36864
	ds_read_b128 v[190:193], v241 offset:32768
	ds_read_b128 v[194:197], v241 offset:36864
	ds_read_b128 v[204:207], v242 offset:32768
	ds_read_b128 v[208:211], v242 offset:36864
	ds_read_b128 v[224:227], v199 offset:32768
	ds_read_b128 v[228:231], v199 offset:36864
	s_waitcnt lgkmcnt(0)
	v_mfma_f32_32x32x16_bf16 v[2:17], v[114:117], v[110:113], v[2:17]
	v_mfma_f32_32x32x16_bf16 v[18:33], v[118:121], v[110:113], v[18:33]
	v_mfma_f32_32x32x16_bf16 v[2:17], v[122:125], v[106:109], v[2:17]
	v_mfma_f32_32x32x16_bf16 v[18:33], v[126:129], v[106:109], v[18:33]
	v_mfma_f32_32x32x16_bf16 v[2:17], v[130:133], v[102:105], v[2:17]
	v_mfma_f32_32x32x16_bf16 v[18:33], v[212:215], v[102:105], v[18:33]
	v_mfma_f32_32x32x16_bf16 v[2:17], v[216:219], v[98:101], v[2:17]
	v_mfma_f32_32x32x16_bf16 v[18:33], v[220:223], v[98:101], v[18:33]
	s_add_i32 s64, s8, 1
	s_and_b64 s[22:23], s[10:11], exec
	s_cselect_b32 s22, s83, s64
	s_lshl_b32 s22, s22, 6
	s_add_u32 s23, s20, s22
	v_cndmask_b32_e64 v114, v82, v83, s[0:1]
	s_addc_u32 s22, s21, 0
	v_mfma_f32_32x32x16_bf16 v[34:49], v[182:185], v[110:113], v[34:49]
	v_mov_b32_dpp v114, v114 quad_perm:[1,0,3,2] row_mask:0xf bank_mask:0xf bound_ctrl:1
	v_cndmask_b32_e64 v83, v83, v114, s[0:1]
	v_cndmask_b32_e64 v82, v114, v82, s[0:1]
	v_cvt_pk_bf16_f32 v114, v82, v83
	v_readfirstlane_b32 s98, v158
	v_readfirstlane_b32 s99, v159
	v_and_b32_e32 v244, 30, v137
	v_lshlrev_b32_e32 v244, 1, v244
	v_lshl_add_u32 v244, v136, 11, v244
	s_lshl_b32 s100, s23, 11
	s_add_u32 s98, s98, s100
	s_addc_u32 s99, s99, 0
	s_add_u32 s100, s98, 0x800
	s_addc_u32 s101, s99, 0
	global_store_dword v244, v114, s[100:101] offset:-2048
	v_mov_b32_e32 v82, v84
	v_mfma_f32_32x32x16_bf16 v[50:65], v[186:189], v[110:113], v[50:65]
	v_cndmask_b32_e64 v83, v82, v85, s[0:1]
	s_add_i32 s8, s8, -1
	s_add_i32 s82, s82, 1
	v_mov_b32_dpp v83, v83 quad_perm:[1,0,3,2] row_mask:0xf bank_mask:0xf bound_ctrl:1
	v_cndmask_b32_e64 v84, v85, v83, s[0:1]
	v_cndmask_b32_e64 v82, v83, v82, s[0:1]
	v_cvt_pk_bf16_f32 v84, v82, v84
	global_store_dword v244, v84, s[100:101] offset:2048
	v_mov_b32_e32 v82, v86
	v_mfma_f32_32x32x16_bf16 v[34:49], v[190:193], v[106:109], v[34:49]
	v_cndmask_b32_e64 v83, v82, v87, s[0:1]
	s_nop 1
	v_mov_b32_dpp v83, v83 quad_perm:[1,0,3,2] row_mask:0xf bank_mask:0xf bound_ctrl:1
	v_cndmask_b32_e64 v84, v87, v83, s[0:1]
	v_cndmask_b32_e64 v82, v83, v82, s[0:1]
	v_cvt_pk_bf16_f32 v84, v82, v84
	s_add_u32 s100, s98, 0x4800
	s_addc_u32 s101, s99, 0
	global_store_dword v244, v84, s[100:101] offset:-2048
	v_mov_b32_e32 v82, v89
	v_mfma_f32_32x32x16_bf16 v[50:65], v[194:197], v[106:109], v[50:65]
	v_cndmask_b32_e64 v83, v88, v82, s[0:1]
	s_nop 1
; DI int crow(int r, int hi) { return (r & 3) + 8 * (r >> 2) + 4 * hi; }
; DI unsigned pkbf(float a, float b) { f32x2 v = {a, b}; bfx2 r = __builtin_convertvector(v, bfx2); return __builtin_bit_cast(unsigned, r); }
; DI void phase_gla_chain(const Params& P, int l, int task0, int ntask_stride, LAS unsigned char* lds) {
;     ...
;             { const int cs = dir ? 63 - n : n; const size_t tokb = (size_t)sq * SEQL + cs * 64; const int odd = lane & 1;
;               bf16_t* ob = OFB + (size_t)dir * MTOK * 1024 + h * 256 + wid * 32 + (r32 & ~1);
; #pragma unroll
;               for (int ib = 0; ib < 2; ++ib)
; #pragma unroll
;                   for (int x = 0; x < 16; x += 2) { float ea_ = o[ib][x], eb_ = o[ib][x + 1]; asm volatile("" : "+v"(ea_), "+v"(eb_)); const float mine = odd ? eb_ : ea_, give = odd ? ea_ : eb_;
;                       const float got = __int_as_float(__builtin_amdgcn_update_dpp(0, __float_as_int(give), 0xB1, 0xF, 0xF, true));
;                       const unsigned w = odd ? pkbf(got, mine) : pkbf(mine, got);
;                       *(unsigned*)(ob + (tokb + ib * 32 + crow(x + odd, hi)) * 1024) = w; } }
	v_mov_b32_dpp v83, v83 quad_perm:[1,0,3,2] row_mask:0xf bank_mask:0xf bound_ctrl:1
	v_cndmask_b32_e64 v82, v82, v83, s[0:1]
	v_cndmask_b32_e64 v83, v83, v88, s[0:1]
	v_cvt_pk_bf16_f32 v84, v83, v82
	global_store_dword v244, v84, s[100:101] offset:2048
	v_mov_b32_e32 v82, v90
	v_mfma_f32_32x32x16_bf16 v[34:49], v[204:207], v[102:105], v[34:49]
	v_cndmask_b32_e64 v83, v82, v91, s[0:1]
	s_nop 1
	v_mov_b32_dpp v83, v83 quad_perm:[1,0,3,2] row_mask:0xf bank_mask:0xf bound_ctrl:1
	v_cndmask_b32_e64 v84, v91, v83, s[0:1]
	v_cndmask_b32_e64 v82, v83, v82, s[0:1]
	v_cvt_pk_bf16_f32 v84, v82, v84
	s_add_u32 s100, s98, 0x8800
	s_addc_u32 s101, s99, 0
	global_store_dword v244, v84, s[100:101] offset:-2048
	v_mov_b32_e32 v82, v92
	v_mfma_f32_32x32x16_bf16 v[50:65], v[208:211], v[102:105], v[50:65]
	v_cndmask_b32_e64 v83, v82, v93, s[0:1]
	s_nop 1
	v_mov_b32_dpp v83, v83 quad_perm:[1,0,3,2] row_mask:0xf bank_mask:0xf bound_ctrl:1
	v_cndmask_b32_e64 v84, v93, v83, s[0:1]
	v_cndmask_b32_e64 v82, v83, v82, s[0:1]
	v_cvt_pk_bf16_f32 v84, v82, v84
	global_store_dword v244, v84, s[100:101] offset:2048
	v_mov_b32_e32 v82, v95
	v_mfma_f32_32x32x16_bf16 v[34:49], v[224:227], v[98:101], v[34:49]
	v_cndmask_b32_e64 v83, v94, v82, s[0:1]
	s_nop 1
	v_mov_b32_dpp v83, v83 quad_perm:[1,0,3,2] row_mask:0xf bank_mask:0xf bound_ctrl:1
	v_cndmask_b32_e64 v82, v82, v83, s[0:1]
	v_cndmask_b32_e64 v83, v83, v94, s[0:1]
	v_cvt_pk_bf16_f32 v84, v83, v82
	s_add_u32 s100, s98, 0xc800
	s_addc_u32 s101, s99, 0
	global_store_dword v244, v84, s[100:101] offset:-2048
	v_mov_b32_e32 v82, v96
	v_mfma_f32_32x32x16_bf16 v[50:65], v[228:231], v[98:101], v[50:65]
	v_cndmask_b32_e64 v83, v82, v97, s[0:1]
	s_nop 1
	v_mov_b32_dpp v83, v83 quad_perm:[1,0,3,2] row_mask:0xf bank_mask:0xf bound_ctrl:1
	v_cndmask_b32_e64 v84, v97, v83, s[0:1]
	v_cndmask_b32_e64 v82, v83, v82, s[0:1]
	v_cvt_pk_bf16_f32 v84, v82, v84
	global_store_dword v244, v84, s[100:101] offset:2048
	s_or_b32 s23, s23, 32
	v_cndmask_b32_e64 v82, v66, v67, s[0:1]
	s_nop 0
	v_mov_b32_dpp v82, v82 quad_perm:[1,0,3,2] row_mask:0xf bank_mask:0xf bound_ctrl:1
	v_cndmask_b32_e64 v67, v67, v82, s[0:1]
	v_cndmask_b32_e64 v66, v82, v66, s[0:1]
	v_cvt_pk_bf16_f32 v82, v66, v67
	s_add_u32 s100, s98, 0x10800
	s_addc_u32 s101, s99, 0
	global_store_dword v244, v82, s[100:101] offset:-2048
	v_mov_b32_e32 v66, v69
	s_nop 0
	v_cndmask_b32_e64 v67, v68, v66, s[0:1]
	s_nop 1
	v_mov_b32_dpp v67, v67 quad_perm:[1,0,3,2] row_mask:0xf bank_mask:0xf bound_ctrl:1
	v_cndmask_b32_e64 v66, v66, v67, s[0:1]
	v_cndmask_b32_e64 v67, v67, v68, s[0:1]
	v_cvt_pk_bf16_f32 v68, v67, v66
	global_store_dword v244, v68, s[100:101] offset:2048
	v_mov_b32_e32 v66, v70
	s_nop 0
	v_cndmask_b32_e64 v67, v66, v71, s[0:1]
	s_nop 1
	v_mov_b32_dpp v67, v67 quad_perm:[1,0,3,2] row_mask:0xf bank_mask:0xf bound_ctrl:1
	v_cndmask_b32_e64 v68, v71, v67, s[0:1]
	v_cndmask_b32_e64 v66, v67, v66, s[0:1]
	v_cvt_pk_bf16_f32 v68, v66, v68
	s_add_u32 s100, s98, 0x14800
	s_addc_u32 s101, s99, 0
	global_store_dword v244, v68, s[100:101] offset:-2048
	v_mov_b32_e32 v66, v72
	s_nop 0
	v_cndmask_b32_e64 v67, v66, v73, s[0:1]
	s_nop 1
	v_mov_b32_dpp v67, v67 quad_perm:[1,0,3,2] row_mask:0xf bank_mask:0xf bound_ctrl:1
	v_cndmask_b32_e64 v68, v73, v67, s[0:1]
	v_cndmask_b32_e64 v66, v67, v66, s[0:1]
	v_cvt_pk_bf16_f32 v68, v66, v68
	global_store_dword v244, v68, s[100:101] offset:2048
	v_mov_b32_e32 v66, v75
	s_nop 0
	v_cndmask_b32_e64 v67, v74, v66, s[0:1]
	s_nop 1
	v_mov_b32_dpp v67, v67 quad_perm:[1,0,3,2] row_mask:0xf bank_mask:0xf bound_ctrl:1
	v_cndmask_b32_e64 v66, v66, v67, s[0:1]
	v_cndmask_b32_e64 v67, v67, v74, s[0:1]
	v_cvt_pk_bf16_f32 v68, v67, v66
	s_add_u32 s100, s98, 0x18800
	s_addc_u32 s101, s99, 0
	global_store_dword v244, v68, s[100:101] offset:-2048
	v_mov_b32_e32 v66, v77
	s_nop 0
	v_cndmask_b32_e64 v67, v76, v66, s[0:1]
	s_nop 1
	v_mov_b32_dpp v67, v67 quad_perm:[1,0,3,2] row_mask:0xf bank_mask:0xf bound_ctrl:1
	v_cndmask_b32_e64 v66, v66, v67, s[0:1]
	v_cndmask_b32_e64 v67, v67, v76, s[0:1]
	v_cvt_pk_bf16_f32 v68, v67, v66
	global_store_dword v244, v68, s[100:101] offset:2048
	v_mov_b32_e32 v66, v78
	s_nop 0
	v_cndmask_b32_e64 v67, v66, v79, s[0:1]
	s_nop 1
	v_mov_b32_dpp v67, v67 quad_perm:[1,0,3,2] row_mask:0xf bank_mask:0xf bound_ctrl:1
	v_cndmask_b32_e64 v68, v79, v67, s[0:1]
	v_cndmask_b32_e64 v66, v67, v66, s[0:1]
	v_cvt_pk_bf16_f32 v68, v66, v68
	s_add_u32 s100, s98, 0x1c800
	s_addc_u32 s101, s99, 0
	global_store_dword v244, v68, s[100:101] offset:-2048
	v_mov_b32_e32 v66, v81
	s_nop 0
	v_cndmask_b32_e64 v67, v80, v66, s[0:1]
	s_nop 1
	v_mov_b32_dpp v67, v67 quad_perm:[1,0,3,2] row_mask:0xf bank_mask:0xf bound_ctrl:1
	v_cndmask_b32_e64 v66, v66, v67, s[0:1]
	v_cndmask_b32_e64 v67, v67, v80, s[0:1]
	v_cvt_pk_bf16_f32 v68, v67, v66
	global_store_dword v244, v68, s[100:101] offset:2048
	s_cmp_eq_u32 s8, -2
	s_cbranch_scc1 .LBB0_965
